# v65 + non-leader workgroups poll the cross-XCD release word directly (no per-XCD relay hop)
# baseline (speedup 1.0000x reference)
.LBB0_186:
	global_atomic_add v4, v187, v237, s[60:61] sc0
	v_cvt_f32_u32_e32 v1, v3
	v_sub_u32_e32 v5, 0, v3
	v_rcp_iflag_f32_e32 v1, v1
	s_nop 0
	v_mul_f32_e32 v1, 0x4f7ffffe, v1
	v_cvt_u32_f32_e32 v1, v1
	v_mul_lo_u32 v5, v5, v1
	v_mul_hi_u32 v5, v1, v5
	v_add_u32_e32 v1, v1, v5
	s_waitcnt vmcnt(0)
	v_mul_hi_u32 v1, v4, v1
	v_mul_lo_u32 v5, v1, v3
	v_sub_u32_e32 v5, v4, v5
	v_add_u32_e32 v6, 1, v1
	v_cmp_ge_u32_e32 vcc, v5, v3
	v_add_u32_e32 v4, 1, v4
	s_nop 0
	v_cndmask_b32_e32 v1, v1, v6, vcc
	v_sub_u32_e32 v6, v5, v3
	v_cndmask_b32_e32 v5, v5, v6, vcc
	v_add_u32_e32 v6, 1, v1
	v_cmp_ge_u32_e32 vcc, v5, v3
	s_nop 1
	v_cndmask_b32_e32 v1, v1, v6, vcc
	v_mul_lo_u32 v5, v3, v1
	v_add_u32_e32 v3, v5, v3
	v_cmp_ne_u32_e32 vcc, v4, v3
	s_and_saveexec_b64 s[8:9], vcc
	s_xor_b64 s[8:9], exec, s[8:9]
	s_cbranch_execz .LBB0_200
	s_waitcnt lgkmcnt(0)
	global_load_dword v2, v187, s[64:65] sc1
	s_waitcnt vmcnt(0)
	v_cmp_eq_u32_e32 vcc, v2, v1
	s_and_saveexec_b64 s[10:11], vcc
	s_cbranch_execz .LBB0_199
	s_mov_b32 s3, 1
	s_mov_b64 s[12:13], 0
	s_branch .LBB0_190

.LBB0_302:
	global_atomic_add v4, v187, v237, s[60:61] sc0
	v_cvt_f32_u32_e32 v1, v3
	v_sub_u32_e32 v5, 0, v3
	v_rcp_iflag_f32_e32 v1, v1
	s_nop 0
	v_mul_f32_e32 v1, 0x4f7ffffe, v1
	v_cvt_u32_f32_e32 v1, v1
	v_mul_lo_u32 v5, v5, v1
	v_mul_hi_u32 v5, v1, v5
	v_add_u32_e32 v1, v1, v5
	s_waitcnt vmcnt(0)
	v_mul_hi_u32 v1, v4, v1
	v_mul_lo_u32 v5, v1, v3
	v_sub_u32_e32 v5, v4, v5
	v_add_u32_e32 v6, 1, v1
	v_cmp_ge_u32_e32 vcc, v5, v3
	v_add_u32_e32 v4, 1, v4
	s_nop 0
	v_cndmask_b32_e32 v1, v1, v6, vcc
	v_sub_u32_e32 v6, v5, v3
	v_cndmask_b32_e32 v5, v5, v6, vcc
	v_add_u32_e32 v6, 1, v1
	v_cmp_ge_u32_e32 vcc, v5, v3
	s_nop 1
	v_cndmask_b32_e32 v1, v1, v6, vcc
	v_mul_lo_u32 v5, v3, v1
	v_add_u32_e32 v3, v5, v3
	v_cmp_ne_u32_e32 vcc, v4, v3
	s_and_saveexec_b64 s[14:15], vcc
	s_xor_b64 s[14:15], exec, s[14:15]
	s_cbranch_execz .LBB0_331
	s_waitcnt lgkmcnt(0)
	global_load_dword v2, v187, s[64:65] sc1
	s_waitcnt vmcnt(0)
	v_cmp_eq_u32_e32 vcc, v2, v1
	s_and_saveexec_b64 s[16:17], vcc
	s_cbranch_execz .LBB0_330
	s_mov_b32 s3, 1
	s_mov_b64 s[18:19], 0
	s_branch .LBB0_306

.LBB0_317:
	global_atomic_add v4, v187, v237, s[60:61] sc0
	v_cvt_f32_u32_e32 v1, v3
	v_sub_u32_e32 v5, 0, v3
	v_rcp_iflag_f32_e32 v1, v1
	s_nop 0
	v_mul_f32_e32 v1, 0x4f7ffffe, v1
	v_cvt_u32_f32_e32 v1, v1
	v_mul_lo_u32 v5, v5, v1
	v_mul_hi_u32 v5, v1, v5
	v_add_u32_e32 v1, v1, v5
	s_waitcnt vmcnt(0)
	v_mul_hi_u32 v1, v4, v1
	v_mul_lo_u32 v5, v1, v3
	v_sub_u32_e32 v5, v4, v5
	v_add_u32_e32 v6, 1, v1
	v_cmp_ge_u32_e32 vcc, v5, v3
	v_add_u32_e32 v4, 1, v4
	s_nop 0
	v_cndmask_b32_e32 v1, v1, v6, vcc
	v_sub_u32_e32 v6, v5, v3
	v_cndmask_b32_e32 v5, v5, v6, vcc
	v_add_u32_e32 v6, 1, v1
	v_cmp_ge_u32_e32 vcc, v5, v3
	s_nop 1
	v_cndmask_b32_e32 v1, v1, v6, vcc
	v_mul_lo_u32 v5, v3, v1
	v_add_u32_e32 v3, v5, v3
	v_cmp_ne_u32_e32 vcc, v4, v3
	s_and_saveexec_b64 s[10:11], vcc
	s_xor_b64 s[10:11], exec, s[10:11]
	s_cbranch_execz .LBB0_348
	s_waitcnt lgkmcnt(0)
	global_load_dword v2, v187, s[64:65] sc1
	s_waitcnt vmcnt(0)
	v_cmp_eq_u32_e32 vcc, v2, v1
	s_and_saveexec_b64 s[12:13], vcc
	s_cbranch_execz .LBB0_347
	s_mov_b32 s3, 1
	s_mov_b64 s[14:15], 0
	s_branch .LBB0_321

.LBB0_525:
	global_atomic_add v4, v187, v237, s[60:61] sc0
	v_cvt_f32_u32_e32 v1, v3
	v_sub_u32_e32 v5, 0, v3
	v_rcp_iflag_f32_e32 v1, v1
	s_nop 0
	v_mul_f32_e32 v1, 0x4f7ffffe, v1
	v_cvt_u32_f32_e32 v1, v1
	v_mul_lo_u32 v5, v5, v1
	v_mul_hi_u32 v5, v1, v5
	v_add_u32_e32 v1, v1, v5
	s_waitcnt vmcnt(0)
	v_mul_hi_u32 v1, v4, v1
	v_mul_lo_u32 v5, v1, v3
	v_sub_u32_e32 v5, v4, v5
	v_add_u32_e32 v6, 1, v1
	v_cmp_ge_u32_e32 vcc, v5, v3
	v_add_u32_e32 v4, 1, v4
	s_nop 0
	v_cndmask_b32_e32 v1, v1, v6, vcc
	v_sub_u32_e32 v6, v5, v3
	v_cndmask_b32_e32 v5, v5, v6, vcc
	v_add_u32_e32 v6, 1, v1
	v_cmp_ge_u32_e32 vcc, v5, v3
	s_nop 1
	v_cndmask_b32_e32 v1, v1, v6, vcc
	v_mul_lo_u32 v5, v3, v1
	v_add_u32_e32 v3, v5, v3
	v_cmp_ne_u32_e32 vcc, v4, v3
	s_and_saveexec_b64 s[6:7], vcc
	s_xor_b64 s[6:7], exec, s[6:7]
	s_cbranch_execz .LBB0_539
	s_waitcnt lgkmcnt(0)
	global_load_dword v2, v187, s[64:65] sc1
	s_waitcnt vmcnt(0)
	v_cmp_eq_u32_e32 vcc, v2, v1
	s_and_saveexec_b64 s[10:11], vcc
	s_cbranch_execz .LBB0_538
	s_mov_b32 s3, 1
	s_mov_b64 s[12:13], 0
	s_branch .LBB0_529

.LBB0_701:
	global_atomic_add v4, v187, v237, s[60:61] sc0
	v_cvt_f32_u32_e32 v1, v3
	v_sub_u32_e32 v5, 0, v3
	v_rcp_iflag_f32_e32 v1, v1
	s_nop 0
	v_mul_f32_e32 v1, 0x4f7ffffe, v1
	v_cvt_u32_f32_e32 v1, v1
	v_mul_lo_u32 v5, v5, v1
	v_mul_hi_u32 v5, v1, v5
	v_add_u32_e32 v1, v1, v5
	s_waitcnt vmcnt(0)
	v_mul_hi_u32 v1, v4, v1
	v_mul_lo_u32 v5, v1, v3
	v_sub_u32_e32 v5, v4, v5
	v_add_u32_e32 v6, 1, v1
	v_cmp_ge_u32_e32 vcc, v5, v3
	v_add_u32_e32 v4, 1, v4
	s_nop 0
	v_cndmask_b32_e32 v1, v1, v6, vcc
	v_sub_u32_e32 v6, v5, v3
	v_cndmask_b32_e32 v5, v5, v6, vcc
	v_add_u32_e32 v6, 1, v1
	v_cmp_ge_u32_e32 vcc, v5, v3
	s_nop 1
	v_cndmask_b32_e32 v1, v1, v6, vcc
	v_mul_lo_u32 v5, v3, v1
	v_add_u32_e32 v3, v5, v3
	v_cmp_ne_u32_e32 vcc, v4, v3
	s_and_saveexec_b64 s[0:1], vcc
	s_xor_b64 s[6:7], exec, s[0:1]
	s_cbranch_execz .LBB0_715
	s_waitcnt lgkmcnt(0)
	global_load_dword v2, v187, s[64:65] sc1
	s_waitcnt vmcnt(0)
	v_cmp_eq_u32_e32 vcc, v2, v1
	s_and_saveexec_b64 s[10:11], vcc
	s_cbranch_execz .LBB0_714
	s_mov_b32 s3, 1
	s_mov_b64 s[12:13], 0
	s_branch .LBB0_705

.LBB0_1073:
	global_atomic_add v4, v187, v237, s[60:61] sc0
	v_cvt_f32_u32_e32 v1, v3
	v_sub_u32_e32 v5, 0, v3
	v_rcp_iflag_f32_e32 v1, v1
	s_nop 0
	v_mul_f32_e32 v1, 0x4f7ffffe, v1
	v_cvt_u32_f32_e32 v1, v1
	v_mul_lo_u32 v5, v5, v1
	v_mul_hi_u32 v5, v1, v5
	v_add_u32_e32 v1, v1, v5
	s_waitcnt vmcnt(0)
	v_mul_hi_u32 v1, v4, v1
	v_mul_lo_u32 v5, v1, v3
	v_sub_u32_e32 v5, v4, v5
	v_add_u32_e32 v6, 1, v1
	v_cmp_ge_u32_e32 vcc, v5, v3
	v_add_u32_e32 v4, 1, v4
	s_nop 0
	v_cndmask_b32_e32 v1, v1, v6, vcc
	v_sub_u32_e32 v6, v5, v3
	v_cndmask_b32_e32 v5, v5, v6, vcc
	v_add_u32_e32 v6, 1, v1
	v_cmp_ge_u32_e32 vcc, v5, v3
	s_nop 1
	v_cndmask_b32_e32 v1, v1, v6, vcc
	v_mul_lo_u32 v5, v3, v1
	v_add_u32_e32 v3, v5, v3
	v_cmp_ne_u32_e32 vcc, v4, v3
	s_and_saveexec_b64 s[0:1], vcc
	s_xor_b64 s[8:9], exec, s[0:1]
	s_cbranch_execz .LBB0_1087
	s_waitcnt lgkmcnt(0)
	global_load_dword v2, v187, s[64:65] sc1
	s_waitcnt vmcnt(0)
	v_cmp_eq_u32_e32 vcc, v2, v1
	s_and_saveexec_b64 s[10:11], vcc
	s_cbranch_execz .LBB0_1086
	s_mov_b32 s3, 1
	s_mov_b64 s[12:13], 0
	s_branch .LBB0_1077

.LBB0_1169:
	global_atomic_add v4, v187, v237, s[60:61] sc0
	v_cvt_f32_u32_e32 v1, v3
	v_sub_u32_e32 v5, 0, v3
	v_rcp_iflag_f32_e32 v1, v1
	s_nop 0
	v_mul_f32_e32 v1, 0x4f7ffffe, v1
	v_cvt_u32_f32_e32 v1, v1
	v_mul_lo_u32 v5, v5, v1
	v_mul_hi_u32 v5, v1, v5
	v_add_u32_e32 v1, v1, v5
	s_waitcnt vmcnt(0)
	v_mul_hi_u32 v1, v4, v1
	v_mul_lo_u32 v5, v1, v3
	v_sub_u32_e32 v5, v4, v5
	v_add_u32_e32 v6, 1, v1
	v_cmp_ge_u32_e32 vcc, v5, v3
	v_add_u32_e32 v4, 1, v4
	s_nop 0
	v_cndmask_b32_e32 v1, v1, v6, vcc
	v_sub_u32_e32 v6, v5, v3
	v_cndmask_b32_e32 v5, v5, v6, vcc
	v_add_u32_e32 v6, 1, v1
	v_cmp_ge_u32_e32 vcc, v5, v3
	s_nop 1
	v_cndmask_b32_e32 v1, v1, v6, vcc
	v_mul_lo_u32 v5, v3, v1
	v_add_u32_e32 v3, v5, v3
	v_cmp_ne_u32_e32 vcc, v4, v3
	s_and_saveexec_b64 s[0:1], vcc
	s_xor_b64 s[6:7], exec, s[0:1]
	s_cbranch_execz .LBB0_1183
	s_waitcnt lgkmcnt(0)
	global_load_dword v2, v187, s[64:65] sc1
	s_waitcnt vmcnt(0)
	v_cmp_eq_u32_e32 vcc, v2, v1
	s_and_saveexec_b64 s[8:9], vcc
	s_cbranch_execz .LBB0_1182
	s_mov_b32 s2, 1
	s_mov_b64 s[10:11], 0
	s_branch .LBB0_1173
